# v027 plus nt hint on the output-projection (P5) epilogue stores, whose consumer (row phase) runs on other XCDs
# baseline (speedup 1.0000x reference)
.LBB0_1102:
	v_mov_b32_e32 v143, v139
	v_mov_b32_e32 v142, v138
	s_ashr_i32 s5, s4, 31
	v_add_u32_e32 v142, s35, v142
	s_lshl_b32 s16, s39, 8
	s_lshl_b64 s[4:5], s[4:5], 19
	s_ashr_i32 s17, s16, 31
	v_cvt_pk_bf16_f32 v68, v68, v69
	v_cvt_pk_bf16_f32 v69, v70, v71
	v_cvt_pk_bf16_f32 v70, v64, v65
	v_add_u32_e32 v64, 0x80, v142
	v_lshlrev_b32_e32 v144, 3, v143
	v_ashrrev_i32_e32 v143, 31, v142
	s_add_u32 s4, s33, s4
	v_cvt_pk_bf16_f32 v108, v108, v109
	v_cvt_pk_bf16_f32 v109, v110, v111
	v_cvt_pk_bf16_f32 v110, v104, v105
	v_add_u32_e32 v104, 16, v142
	v_ashrrev_i32_e32 v65, 31, v64
	v_cvt_pk_bf16_f32 v44, v44, v45
	v_cvt_pk_bf16_f32 v45, v46, v47
	v_cvt_pk_bf16_f32 v46, v40, v41
	v_add_u32_e32 v40, 0x90, v142
	s_addc_u32 s5, s34, s5
	v_lshlrev_b64 v[146:147], 11, v[142:143]
	v_ashrrev_i32_e32 v105, 31, v104
	v_cvt_pk_bf16_f32 v92, v92, v93
	v_cvt_pk_bf16_f32 v93, v94, v95
	v_cvt_pk_bf16_f32 v94, v88, v89
	v_add_u32_e32 v88, 32, v142
	v_lshlrev_b64 v[64:65], 11, v[64:65]
	v_ashrrev_i32_e32 v41, 31, v40
	v_cvt_pk_bf16_f32 v28, v28, v29
	v_cvt_pk_bf16_f32 v29, v30, v31
	v_cvt_pk_bf16_f32 v30, v24, v25
	v_add_u32_e32 v24, 0xa0, v142
	v_lshl_add_u64 v[146:147], s[4:5], 0, v[146:147]
	s_lshl_b64 s[16:17], s[16:17], 1
	v_lshlrev_b64 v[104:105], 11, v[104:105]
	v_ashrrev_i32_e32 v89, 31, v88
	v_cvt_pk_bf16_f32 v76, v76, v77
	v_cvt_pk_bf16_f32 v77, v78, v79
	v_cvt_pk_bf16_f32 v78, v72, v73
	v_add_u32_e32 v72, 48, v142
	v_lshl_add_u64 v[64:65], s[4:5], 0, v[64:65]
	v_lshlrev_b64 v[40:41], 11, v[40:41]
	v_ashrrev_i32_e32 v25, 31, v24
	v_cvt_pk_bf16_f32 v12, v12, v13
	v_cvt_pk_bf16_f32 v13, v14, v15
	v_cvt_pk_bf16_f32 v14, v8, v9
	v_add_u32_e32 v8, 0xb0, v142
	v_ashrrev_i32_e32 v145, 31, v144
	v_lshl_add_u64 v[146:147], v[146:147], 0, s[16:17]
	v_lshl_add_u64 v[104:105], s[4:5], 0, v[104:105]
	v_lshlrev_b64 v[88:89], 11, v[88:89]
	v_ashrrev_i32_e32 v73, 31, v72
	v_lshl_add_u64 v[64:65], v[64:65], 0, s[16:17]
	v_lshl_add_u64 v[40:41], s[4:5], 0, v[40:41]
	v_lshlrev_b64 v[24:25], 11, v[24:25]
	v_ashrrev_i32_e32 v9, 31, v8
	v_lshl_add_u64 v[146:147], v[146:147], 0, s[40:41]
	v_lshlrev_b64 v[144:145], 1, v[144:145]
	v_lshl_add_u64 v[104:105], v[104:105], 0, s[16:17]
	v_lshl_add_u64 v[88:89], s[4:5], 0, v[88:89]
	v_lshlrev_b64 v[72:73], 11, v[72:73]
	v_lshl_add_u64 v[64:65], v[64:65], 0, s[40:41]
	v_lshl_add_u64 v[40:41], v[40:41], 0, s[16:17]
	v_lshl_add_u64 v[24:25], s[4:5], 0, v[24:25]
	v_lshlrev_b64 v[8:9], 11, v[8:9]
	v_lshl_add_u64 v[146:147], v[146:147], 0, v[144:145]
	v_cvt_pk_bf16_f32 v111, v106, v107
	v_lshl_add_u64 v[104:105], v[104:105], 0, s[40:41]
	v_lshl_add_u64 v[88:89], v[88:89], 0, s[16:17]
	v_lshl_add_u64 v[72:73], s[4:5], 0, v[72:73]
	v_lshl_add_u64 v[64:65], v[64:65], 0, v[144:145]
	v_cvt_pk_bf16_f32 v47, v42, v43
	v_lshl_add_u64 v[40:41], v[40:41], 0, s[40:41]
	v_lshl_add_u64 v[24:25], v[24:25], 0, s[16:17]
	v_lshl_add_u64 v[8:9], s[4:5], 0, v[8:9]
	flat_store_dwordx4 v[146:147], v[108:111] offset:256 nt
	v_cvt_pk_bf16_f32 v95, v90, v91
	v_lshl_add_u64 v[88:89], v[88:89], 0, s[40:41]
	v_lshl_add_u64 v[108:109], v[104:105], 0, v[144:145]
	v_lshl_add_u64 v[72:73], v[72:73], 0, s[16:17]
	flat_store_dwordx4 v[64:65], v[44:47] offset:256 nt
	v_cvt_pk_bf16_f32 v31, v26, v27
	v_lshl_add_u64 v[24:25], v[24:25], 0, s[40:41]
	v_lshl_add_u64 v[44:45], v[40:41], 0, v[144:145]
	v_lshl_add_u64 v[8:9], v[8:9], 0, s[16:17]
	flat_store_dwordx4 v[108:109], v[92:95] offset:256 nt
	v_cvt_pk_bf16_f32 v79, v74, v75
	v_lshl_add_u64 v[72:73], v[72:73], 0, s[40:41]
	v_lshl_add_u64 v[92:93], v[88:89], 0, v[144:145]
	flat_store_dwordx4 v[44:45], v[28:31] offset:256 nt
	v_cvt_pk_bf16_f32 v15, v10, v11
	v_lshl_add_u64 v[8:9], v[8:9], 0, s[40:41]
	v_lshl_add_u64 v[28:29], v[24:25], 0, v[144:145]
	v_cvt_pk_bf16_f32 v124, v124, v125
	v_cvt_pk_bf16_f32 v125, v126, v127
	v_cvt_pk_bf16_f32 v126, v120, v121
	v_cvt_pk_bf16_f32 v127, v122, v123
	v_cvt_pk_bf16_f32 v104, v116, v117
	v_cvt_pk_bf16_f32 v105, v118, v119
	v_cvt_pk_bf16_f32 v106, v112, v113
	v_cvt_pk_bf16_f32 v107, v114, v115
	v_cvt_pk_bf16_f32 v88, v100, v101
	v_cvt_pk_bf16_f32 v89, v102, v103
	v_cvt_pk_bf16_f32 v90, v96, v97
	v_cvt_pk_bf16_f32 v91, v98, v99
	flat_store_dwordx4 v[92:93], v[76:79] offset:256 nt
	v_cvt_pk_bf16_f32 v74, v80, v81
	v_cvt_pk_bf16_f32 v75, v82, v83
	v_lshl_add_u64 v[76:77], v[72:73], 0, v[144:145]
	v_cvt_pk_bf16_f32 v72, v84, v85
	v_cvt_pk_bf16_f32 v73, v86, v87
	v_cvt_pk_bf16_f32 v71, v66, v67
	v_cvt_pk_bf16_f32 v60, v60, v61
	v_cvt_pk_bf16_f32 v61, v62, v63
	v_cvt_pk_bf16_f32 v62, v56, v57
	v_cvt_pk_bf16_f32 v63, v58, v59
	v_cvt_pk_bf16_f32 v40, v52, v53
	v_cvt_pk_bf16_f32 v41, v54, v55
	v_cvt_pk_bf16_f32 v42, v48, v49
	v_cvt_pk_bf16_f32 v43, v50, v51
	v_cvt_pk_bf16_f32 v24, v36, v37
	v_cvt_pk_bf16_f32 v25, v38, v39
	v_cvt_pk_bf16_f32 v26, v32, v33
	v_cvt_pk_bf16_f32 v27, v34, v35
	flat_store_dwordx4 v[28:29], v[12:15] offset:256 nt
	v_cvt_pk_bf16_f32 v10, v16, v17
	v_cvt_pk_bf16_f32 v11, v18, v19
	v_lshl_add_u64 v[12:13], v[8:9], 0, v[144:145]
	v_cvt_pk_bf16_f32 v8, v20, v21
	v_cvt_pk_bf16_f32 v9, v22, v23
	v_cvt_pk_bf16_f32 v4, v4, v5
	v_cvt_pk_bf16_f32 v5, v6, v7
	v_cvt_pk_bf16_f32 v6, v0, v1
	v_cvt_pk_bf16_f32 v7, v2, v3
	s_andn2_b64 vcc, exec, s[6:7]
	s_mov_b64 s[4:5], -1
	flat_store_dwordx4 v[146:147], v[124:127] nt
	flat_store_dwordx4 v[108:109], v[104:107] nt
	flat_store_dwordx4 v[92:93], v[88:91] nt
	flat_store_dwordx4 v[76:77], v[72:75] nt
	flat_store_dwordx4 v[76:77], v[68:71] offset:256 nt
	flat_store_dwordx4 v[64:65], v[60:63] nt
	flat_store_dwordx4 v[44:45], v[40:43] nt
	flat_store_dwordx4 v[28:29], v[24:27] nt
	flat_store_dwordx4 v[12:13], v[8:11] nt
	flat_store_dwordx4 v[12:13], v[4:7] offset:256 nt
	s_cbranch_vccnz .LBB0_1091
	s_andn2_b64 vcc, exec, s[0:1]
	s_cbranch_vccnz .LBB0_1090
	s_barrier
	s_branch .LBB0_1090
